# scan2 chain step restructured: next segment's T/L operands prefetched during the MFMAs, LDS-DMA refill and state stores issued inside the MFMA stream
# speedup vs baseline: 1.0755x; 1.0113x over previous
; __device__ __forceinline__ void lds_barrier() { asm volatile("s_waitcnt lgkmcnt(0)" ::: "memory"); __builtin_amdgcn_s_barrier(); asm volatile("" ::: "memory"); }
; #define CH_WAIT(n) asm volatile("s_waitcnt vmcnt(" #n ")" ::: "memory")
; __device__ __forceinline__ void phase_scan2(const Params& p, const Lt& lt, int nblk, unsigned char* lds) {
;     ...
;         f32x4 s4 = {0.f, 0.f, 0.f, 0.f};
;         int slot = 0;
; #pragma unroll 1
;         for (int g = 0; g < NSEG; ++g) {
;             if (w < 4) CH_WAIT(28); else CH_WAIT(8);
;             lds_barrier();
;             { const int fs = slot == 0 ? D - 1 : slot - 1; CH_DMA(g + D - 1, fs); }
;             if (w < 4) {
; #pragma unroll
;                 for (int r = 0; r < 4; ++r) So[(size_t)g * 4096 + r * 64] = s4[r];
;                 const float* As = Sx + (g & 1) * 16 * SP + fi * SP + fq;
;                 const float* Bs = Rg + slot * SLOTF + fq * 64 + 16 * w + fi;
;                 const float* Lr = Rg + slot * SLOTF + 4096 + (4 * fq) * 64 + 16 * w + fi;
;                 float av[16], bv[16];
; #pragma unroll
;                 for (int ks = 0; ks < 16; ++ks) { av[ks] = As[4 * ks]; bv[ks] = Bs[(4 * ks) * 64]; }
;                 f32x4 c0 = {Lr[0], Lr[64], Lr[128], Lr[192]}, c1 = {0.f, 0.f, 0.f, 0.f};
.LBB0_161:
	s_lshl_b32 s10, s45, 2
	s_and_b32 s10, s10, 0x3000
	s_waitcnt vmcnt(0)
	v_lshl_or_b32 v5, v18, 2, s10
	s_waitcnt lgkmcnt(0)
	s_barrier
	v_or_b32_e32 v12, s28, v5
	v_mov_b32_e32 v13, s29
	v_lshl_add_u64 v[12:13], v[6:7], 0, v[12:13]
	v_mov_b32_e32 v16, v3
	v_mov_b32_e32 v17, v3
	v_mov_b32_e32 v14, v3
	v_mov_b32_e32 v15, v3
	s_mov_b32 s30, 0
	s_mov_b32 s31, 0
	s_mov_b32 s51, 0
	v_add3_u32 v94, s49, v20, v4
	v_add3_u32 v95, s49, v18, v4
	ds_read2st64_b32 v[24:25], v94 offset0:64 offset1:65
	ds_read2st64_b32 v[26:27], v94 offset0:66 offset1:67
	ds_read2st64_b32 v[56:57], v95 offset0:0 offset1:4
	ds_read2st64_b32 v[58:59], v95 offset0:8 offset1:12
	ds_read2st64_b32 v[60:61], v95 offset0:16 offset1:20
	ds_read2st64_b32 v[62:63], v95 offset0:24 offset1:28
	ds_read2st64_b32 v[64:65], v95 offset0:32 offset1:36
	ds_read2st64_b32 v[66:67], v95 offset0:40 offset1:44
	ds_read2st64_b32 v[68:69], v95 offset0:48 offset1:52
	ds_read2st64_b32 v[70:71], v95 offset0:56 offset1:60
	s_branch .LBB0_163

; __device__ __forceinline__ void lds_barrier() { asm volatile("s_waitcnt lgkmcnt(0)" ::: "memory"); __builtin_amdgcn_s_barrier(); asm volatile("" ::: "memory"); }
; #define CH_WAIT(n) asm volatile("s_waitcnt vmcnt(" #n ")" ::: "memory")
; __device__ __forceinline__ void phase_scan2(const Params& p, const Lt& lt, int nblk, unsigned char* lds) {
;     ...
;         for (int g = 0; g < NSEG; ++g) {
;             if (w < 4) CH_WAIT(28); else CH_WAIT(8);
;             lds_barrier();
;             { const int fs = slot == 0 ? D - 1 : slot - 1; CH_DMA(g + D - 1, fs); }
;             if (w < 4) {
; #pragma unroll
;                 for (int r = 0; r < 4; ++r) So[(size_t)g * 4096 + r * 64] = s4[r];
;                 const float* As = Sx + (g & 1) * 16 * SP + fi * SP + fq;
;                 const float* Bs = Rg + slot * SLOTF + fq * 64 + 16 * w + fi;
;                 const float* Lr = Rg + slot * SLOTF + 4096 + (4 * fq) * 64 + 16 * w + fi;
;                 float av[16], bv[16];
; #pragma unroll
;                 for (int ks = 0; ks < 16; ++ks) { av[ks] = As[4 * ks]; bv[ks] = Bs[(4 * ks) * 64]; }
;                 f32x4 c0 = {Lr[0], Lr[64], Lr[128], Lr[192]}, c1 = {0.f, 0.f, 0.f, 0.f};
;                 asm volatile("s_waitcnt lgkmcnt(0)" ::: "memory");
; #pragma unroll
;                 for (int ks = 0; ks < 16; ks += 2) {
;                     c0 = __builtin_amdgcn_mfma_f32_16x16x4f32(av[ks], bv[ks], c0, 0, 0, 0);
;                     c1 = __builtin_amdgcn_mfma_f32_16x16x4f32(av[ks + 1], bv[ks + 1], c1, 0, 0, 0);
;                 }
;                 s4 = c0 + c1;
;                 float* Sn = Sx + ((g + 1) & 1) * 16 * SP + (4 * fq) * SP + 16 * w + fi;
; #pragma unroll
;                 for (int r = 0; r < 4; ++r) Sn[r * SP] = s4[r];
;             }
.LBB0_163:
	s_and_b64 vcc, exec, s[8:9]
	s_cbranch_vccz .Lsc2_w25
	s_waitcnt vmcnt(6)
	s_branch .Lsc2_wd
.Lsc2_w25:
	s_waitcnt vmcnt(25)
.Lsc2_wd:
	s_mul_i32 s28, s31, 0x5000
	s_min_u32 s10, s51, 0x79
	s_add_i32 s29, s28, 0xffffb000
	s_cmp_lg_u32 s31, 0
	s_cselect_b32 s29, s29, 0x19000
	s_lshl_b32 s10, s10, 12
	s_addk_i32 s10, 0x5000
	s_lshl_b32 s10, s10, 2
	s_add_i32 s52, s29, s37
	s_mov_b64 s[54:55], 0x400
	s_waitcnt lgkmcnt(0)
	s_barrier
	s_and_b64 vcc, exec, s[4:5]
	s_cbranch_vccz .Lsc2_compute
	v_lshl_add_u64 v[92:93], v[8:9], 0, s[10:11]
	s_mov_b32 m0, s52
	s_nop 0
	global_load_lds_dwordx4 v[92:93], off
	v_lshl_add_u64 v[92:93], v[92:93], 0, s[54:55]
	s_add_i32 m0, s52, 0x400
	s_nop 0
	global_load_lds_dwordx4 v[92:93], off
	s_branch .LBB0_162
.Lsc2_compute:
	s_and_b32 s53, s30, 16
	s_mul_i32 vcc_lo, s53, 0x108
	v_add_u32_e32 v5, vcc_lo, v19
	ds_read2_b32 v[40:41], v5 offset0:0 offset1:4
	ds_read2_b32 v[42:43], v5 offset0:8 offset1:12
	ds_read2_b32 v[44:45], v5 offset0:16 offset1:20
	ds_read2_b32 v[46:47], v5 offset0:24 offset1:28
	ds_read2_b32 v[48:49], v5 offset0:32 offset1:36
	ds_read2_b32 v[50:51], v5 offset0:40 offset1:44
	ds_read2_b32 v[52:53], v5 offset0:48 offset1:52
	ds_read2_b32 v[54:55], v5 offset0:56 offset1:60
	s_xor_b32 s53, s53, 16
	s_mulk_i32 s53, 0x108
	v_add_u32_e32 v5, s53, v21
	s_add_i32 s53, s28, 0x5000
	s_cmp_eq_u32 s31, 5
	s_cselect_b32 s53, 0, s53
	s_add_i32 s53, s49, s53
	v_add3_u32 v94, s53, v20, v4
	v_add3_u32 v95, s53, v18, v4
	v_lshl_add_u64 v[92:93], v[8:9], 0, s[10:11]
	v_lshl_add_u64 v[96:97], v[92:93], 0, s[54:55]
	v_lshl_add_u64 v[98:99], v[10:11], 0, s[10:11]
	s_add_i32 s53, s29, s38
	s_add_i32 s53, s53, 0x4000
	s_bitcmp1_b32 s30, 4
	s_cbranch_scc1 .Lsc2_odd
	s_waitcnt lgkmcnt(0)
	v_mfma_f32_16x16x4_f32 v[24:27], v40, v56, v[24:27]
	v_mfma_f32_16x16x4_f32 v[28:31], v41, v57, 0
	s_mov_b32 m0, s52
	s_nop 0
	global_load_lds_dwordx4 v[92:93], off
	s_add_i32 m0, s52, 0x400
	v_mfma_f32_16x16x4_f32 v[24:27], v42, v58, v[24:27]
	v_mfma_f32_16x16x4_f32 v[28:31], v43, v59, v[28:31]
	global_load_lds_dwordx4 v[96:97], off
	s_mov_b32 m0, s53
	v_mfma_f32_16x16x4_f32 v[24:27], v44, v60, v[24:27]
	v_mfma_f32_16x16x4_f32 v[28:31], v45, v61, v[28:31]
	global_load_lds_dwordx4 v[98:99], off
	global_store_dword v[12:13], v16, off offset:-512
	global_store_dword v[12:13], v17, off offset:-256
	v_mfma_f32_16x16x4_f32 v[24:27], v46, v62, v[24:27]
	v_mfma_f32_16x16x4_f32 v[28:31], v47, v63, v[28:31]
	global_store_dword v[12:13], v14, off
	global_store_dword v[12:13], v15, off offset:256
	ds_read2st64_b32 v[72:73], v94 offset0:64 offset1:65
	ds_read2st64_b32 v[74:75], v94 offset0:66 offset1:67
	v_mfma_f32_16x16x4_f32 v[24:27], v48, v64, v[24:27]
	v_mfma_f32_16x16x4_f32 v[28:31], v49, v65, v[28:31]
	ds_read2st64_b32 v[76:77], v95 offset0:0 offset1:4
	ds_read2st64_b32 v[78:79], v95 offset0:8 offset1:12
	v_mfma_f32_16x16x4_f32 v[24:27], v50, v66, v[24:27]
	v_mfma_f32_16x16x4_f32 v[28:31], v51, v67, v[28:31]
	ds_read2st64_b32 v[80:81], v95 offset0:16 offset1:20
	ds_read2st64_b32 v[82:83], v95 offset0:24 offset1:28
	v_mfma_f32_16x16x4_f32 v[24:27], v52, v68, v[24:27]
	v_mfma_f32_16x16x4_f32 v[28:31], v53, v69, v[28:31]
	ds_read2st64_b32 v[84:85], v95 offset0:32 offset1:36
	ds_read2st64_b32 v[86:87], v95 offset0:40 offset1:44
	v_mfma_f32_16x16x4_f32 v[24:27], v54, v70, v[24:27]
	v_mfma_f32_16x16x4_f32 v[28:31], v55, v71, v[28:31]
	ds_read2st64_b32 v[88:89], v95 offset0:48 offset1:52
	ds_read2st64_b32 v[90:91], v95 offset0:56 offset1:60
	s_nop 9
	v_pk_add_f32 v[14:15], v[26:27], v[30:31]
	v_pk_add_f32 v[16:17], v[24:25], v[28:29]
	ds_write2_b32 v5, v16, v17 offset1:66
	ds_write2_b32 v5, v14, v15 offset0:132 offset1:198
	s_branch .LBB0_162
.Lsc2_odd:
	s_waitcnt lgkmcnt(0)
	v_mfma_f32_16x16x4_f32 v[72:75], v40, v76, v[72:75]
	v_mfma_f32_16x16x4_f32 v[28:31], v41, v77, 0
	s_mov_b32 m0, s52
	s_nop 0
	global_load_lds_dwordx4 v[92:93], off
	s_add_i32 m0, s52, 0x400
	v_mfma_f32_16x16x4_f32 v[72:75], v42, v78, v[72:75]
	v_mfma_f32_16x16x4_f32 v[28:31], v43, v79, v[28:31]
	global_load_lds_dwordx4 v[96:97], off
	s_mov_b32 m0, s53
	v_mfma_f32_16x16x4_f32 v[72:75], v44, v80, v[72:75]
	v_mfma_f32_16x16x4_f32 v[28:31], v45, v81, v[28:31]
	global_load_lds_dwordx4 v[98:99], off
	global_store_dword v[12:13], v16, off offset:-512
	global_store_dword v[12:13], v17, off offset:-256
	v_mfma_f32_16x16x4_f32 v[72:75], v46, v82, v[72:75]
	v_mfma_f32_16x16x4_f32 v[28:31], v47, v83, v[28:31]
	global_store_dword v[12:13], v14, off
	global_store_dword v[12:13], v15, off offset:256
	ds_read2st64_b32 v[24:25], v94 offset0:64 offset1:65
	ds_read2st64_b32 v[26:27], v94 offset0:66 offset1:67
	v_mfma_f32_16x16x4_f32 v[72:75], v48, v84, v[72:75]
	v_mfma_f32_16x16x4_f32 v[28:31], v49, v85, v[28:31]
	ds_read2st64_b32 v[56:57], v95 offset0:0 offset1:4
	ds_read2st64_b32 v[58:59], v95 offset0:8 offset1:12
	v_mfma_f32_16x16x4_f32 v[72:75], v50, v86, v[72:75]
	v_mfma_f32_16x16x4_f32 v[28:31], v51, v87, v[28:31]
	ds_read2st64_b32 v[60:61], v95 offset0:16 offset1:20
	ds_read2st64_b32 v[62:63], v95 offset0:24 offset1:28
	v_mfma_f32_16x16x4_f32 v[72:75], v52, v88, v[72:75]
	v_mfma_f32_16x16x4_f32 v[28:31], v53, v89, v[28:31]
	ds_read2st64_b32 v[64:65], v95 offset0:32 offset1:36
	ds_read2st64_b32 v[66:67], v95 offset0:40 offset1:44
	v_mfma_f32_16x16x4_f32 v[72:75], v54, v90, v[72:75]
	v_mfma_f32_16x16x4_f32 v[28:31], v55, v91, v[28:31]
	ds_read2st64_b32 v[68:69], v95 offset0:48 offset1:52
	ds_read2st64_b32 v[70:71], v95 offset0:56 offset1:60
	s_nop 9
	v_pk_add_f32 v[14:15], v[74:75], v[30:31]
	v_pk_add_f32 v[16:17], v[72:73], v[28:29]
	ds_write2_b32 v5, v16, v17 offset1:66
	ds_write2_b32 v5, v14, v15 offset0:132 offset1:198
	s_branch .LBB0_162
